# adds: DFT stage-2 units rotated across CUs by 32*wave so every CU gets 4 long + 4 short units
# baseline (speedup 1.0000x reference)
.LBB0_587:
	s_or_b64 exec, exec, s[0:1]
	v_readlane_b32 s4, v254, 19
	v_readlane_b32 s0, v254, 14
	v_readlane_b32 s5, v254, 20
	s_lshl_b32 s27, s26, 17
	s_lshl_b32 s40, s41, 8
	s_add_i32 s40, s40, s0
	s_and_b32 s40, s40, 0x7ff
	s_add_i32 s40, s40, s41
	s_mov_b64 s[0:1], -1
	s_and_b64 vcc, exec, s[4:5]
	s_waitcnt lgkmcnt(0)
	s_barrier
	s_cbranch_vccz .LBB0_669
	s_cmpk_gt_i32 s40, 0x83f
	s_movk_i32 s6, 0x110
	s_movk_i32 s7, 0x220
	s_movk_i32 s16, 0x440
	s_cbranch_scc1 .LBB0_668
	s_bfe_u32 s0, s18, 0x30006
	s_lshl_b32 s1, s0, 14
	s_mul_i32 s4, s41, 0x2200
	s_lshl_b32 s56, s0, 6
	s_or_b32 s1, s1, s27
	s_add_i32 s57, s4, 0
	v_readlane_b32 s4, v254, 21
	s_add_u32 s12, s4, s1
	v_readlane_b32 s1, v254, 22
	s_addc_u32 s13, s1, 0
	s_lshl_b32 s0, s0, 7
	v_readlane_b32 s1, v254, 23
	s_add_u32 s68, s1, s0
	v_readlane_b32 s1, v254, 24
	s_addc_u32 s69, s1, 0
	v_readlane_b32 s4, v255, 17
	v_readlane_b32 s5, v255, 18
	s_add_u32 s38, s4, s0
	s_addc_u32 s39, s5, 0
	s_mov_b32 s70, s40
	s_branch .LBB0_591
